# one s_nop 0 at the diff-unit loop head: all following code (attention loops, Wo, FFN2) shifted by 4 bytes (placement phase test)
# baseline (speedup 1.0000x reference)
; __device__ __forceinline__ void diff_unit(int b, int hd, int qb, const bf16_t* Q, const bf16_t* K, const bf16_t* VT, bf16_t* O, const float* biasd, float lam, const float* subg, ALAS unsigned char* lds) {
;     int tid_ = threadIdx.x; asm volatile("" : "+v"(tid_));
;     const int tid = tid_, lane = tid & 63, wid = __builtin_amdgcn_readfirstlane(tid >> 6), r32 = lane & 31, hi = lane >> 5;
;     const int map = wid >> 2, w4 = wid & 3, q0 = qb * 128 + w4 * 32, qpos = q0 + r32;
;     if (wid >= 4) __builtin_amdgcn_s_setprio(1);
.LBB0_495:
	s_nop 0
	v_mov_b32_e32 v135, v200
	s_nop 0
	v_readfirstlane_b32 s7, v135
	s_ashr_i32 s4, s7, 6
	s_cmp_lt_i32 s4, 4
	s_cbranch_scc1 .LBB0_497
	s_setprio 1
